# + m10: grid barrier cross-XCD level waits on the arrival counter itself (no separate release word): one memory round trip less per barrier
# baseline (speedup 1.0000x reference)
; __device__ __forceinline__ unsigned xb_ld(unsigned* p)              { return __hip_atomic_load(p, __ATOMIC_RELAXED, __HIP_MEMORY_SCOPE_AGENT); }
; __device__ __forceinline__ unsigned xb_add(unsigned* p, unsigned v) { return __hip_atomic_fetch_add(p, v, __ATOMIC_RELAXED, __HIP_MEMORY_SCOPE_AGENT); }
; #define XB_SPIN(cond, bar) do { unsigned _sp = 0; while (cond) { __builtin_amdgcn_s_sleep(0); \
;     if ((++_sp & 255u) == 0u) { if (xb_ld(&(bar)[XB_TMO])) break; if (_sp > XB_SPIN_CAP) { atomicAdd(&(bar)[XB_TMO], 1u); break; } } } } while (0)
; __device__ __forceinline__ void xcd_barrier(const XcdBarrier& b) {
;     ...
;         const unsigned old = xb_add(&bar[XB_XSUB(b.x)], 1u);
;         const unsigned gen = old / nloc;
;         if (old + 1u == (gen + 1u) * nloc) {
;             __builtin_amdgcn_fence(__ATOMIC_RELEASE, "agent");
;             asm volatile("s_waitcnt vmcnt(0)" ::: "memory");
;             const unsigned og = xb_add(&bar[XB_TOP], 1u);
;             const unsigned tg = og / nx;
;             if (og + 1u == (tg + 1u) * nx) xb_add(&bar[XB_TOPGEN], 1u);
;             else XB_SPIN(xb_ld(&bar[XB_TOPGEN]) == tg, bar);
;             __builtin_amdgcn_fence(__ATOMIC_ACQUIRE, "agent");
;             xb_add(&bar[XB_XGEN(b.x)], 1u);
;             asm volatile("s_waitcnt vmcnt(0)" ::: "memory");
.LBB0_759:
	s_or_b64 exec, exec, s[12:13]
	v_cvt_f32_u32_e32 v3, v0
	s_waitcnt vmcnt(0)
	v_readfirstlane_b32 s1, v2
	s_add_u32 s10, s30, 0x83500
	s_addc_u32 s11, s31, 0
	v_rcp_iflag_f32_e32 v3, v3
	v_add_u32_e32 v1, s1, v1
	v_add_u32_e32 v4, 1, v1
	s_mov_b64 s[14:15], 0
	v_mul_f32_e32 v2, 0x4f7ffffe, v3
	v_cvt_u32_f32_e32 v2, v2
	v_sub_u32_e32 v3, 0, v0
	v_mul_lo_u32 v3, v3, v2
	v_mul_hi_u32 v3, v2, v3
	v_add_u32_e32 v2, v2, v3
	v_mul_hi_u32 v2, v1, v2
	v_mul_lo_u32 v3, v2, v0
	v_sub_u32_e32 v1, v1, v3
	v_add_u32_e32 v5, 1, v2
	v_cmp_ge_u32_e32 vcc, v1, v0
	v_sub_u32_e32 v3, v1, v0
	s_nop 0
	v_cndmask_b32_e32 v2, v2, v5, vcc
	v_cndmask_b32_e32 v1, v1, v3, vcc
	v_add_u32_e32 v3, 1, v2
	v_cmp_ge_u32_e32 vcc, v1, v0
	s_nop 1
	v_cndmask_b32_e32 v2, v2, v3, vcc
	v_mul_lo_u32 v1, v0, v2
	v_add_u32_e32 v0, v1, v0
	v_mov_b32_e32 v5, v0
	v_cmp_ne_u32_e32 vcc, v4, v0
	v_mov_b64_e32 v[0:1], s[10:11]
	s_and_saveexec_b64 s[12:13], vcc
	s_cbranch_execz .LBB0_771
	global_load_dword v0, v193, s[10:11] offset:-256 sc1
	s_mov_b64 s[18:19], 0
	s_waitcnt vmcnt(0)
	v_cmp_lt_u32_e32 vcc, v0, v5
	s_and_saveexec_b64 s[16:17], vcc
	s_cbranch_execz .LBB0_770
	s_add_u32 s14, s30, 0x80200
	s_addc_u32 s15, s31, 0
	s_mov_b32 s1, 1
	s_branch .LBB0_763

; __device__ __forceinline__ unsigned xb_ld(unsigned* p)              { return __hip_atomic_load(p, __ATOMIC_RELAXED, __HIP_MEMORY_SCOPE_AGENT); }
; #define XB_SPIN(cond, bar) do { unsigned _sp = 0; while (cond) { __builtin_amdgcn_s_sleep(0); \
;     if ((++_sp & 255u) == 0u) { if (xb_ld(&(bar)[XB_TMO])) break; if (_sp > XB_SPIN_CAP) { atomicAdd(&(bar)[XB_TMO], 1u); break; } } } } while (0)
; __device__ __forceinline__ void xcd_barrier(const XcdBarrier& b) {
;     ...
;             else XB_SPIN(xb_ld(&bar[XB_TOPGEN]) == tg, bar);
.LBB0_767:
	global_load_dword v0, v193, s[10:11] offset:-256 sc1
	s_add_i32 s1, s1, 1
	s_mov_b64 s[28:29], -1
	s_waitcnt vmcnt(0)
	v_cmp_ge_u32_e32 vcc, v0, v5
	s_orn2_b64 s[22:23], vcc, exec
	s_branch .LBB0_762
